# rmsnorm row loop: eight loop-invariant norm-weight vectors cached in registers (removes the second dependent memory round trip per row)
# baseline (speedup 1.0000x reference)
; #define TIDX ((int)((wave_s << 6) | lane_id_v()))
; __device__ __forceinline__ void phase_rmsnorm(const float* __restrict__ src_meta, const float* __restrict__ src_body, const float* __restrict__ w, bf16_t* __restrict__ H, const int wave_s) {
;   int t_ = TIDX; asm volatile("" : "+v"(t_)); const int lane = t_ & 63, wave = __builtin_amdgcn_readfirstlane(t_ >> 6), gw = blockIdx.x * 8 + wave, NGW = gridDim.x * 8; (void)wave;
;   for (int r = gw; r < MP; r += NGW) {
;     u32x2* o8 = (u32x2*)(H + (size_t)r * DM) + lane;
;     ...
;     for (int j = 0; j < 8; ++j) { const f32x4 g = ((const f32x4*)w)[lane + 64 * j];
.LBB0_74:
	s_and_b64 s[0:1], s[68:69], exec
	v_readlane_b32 s24, v254, 7
	v_readlane_b32 s0, v251, 3
	v_readlane_b32 s27, v254, 10
	s_cselect_b32 s0, s27, s0
	v_readlane_b32 s26, v254, 9
	v_writelane_b32 v255, s0, 3
	v_readlane_b32 s0, v251, 2
	s_cselect_b32 s0, s26, s0
	v_readlane_b32 s25, v254, 8
	v_writelane_b32 v255, s0, 4
	v_readlane_b32 s0, v254, 11
	v_readlane_b32 s1, v254, 12
	v_readlane_b32 s2, v254, 13
	v_readlane_b32 s3, v254, 14
	s_cselect_b32 s1, s25, s3
	s_cselect_b32 s0, s24, s2
	v_mbcnt_lo_u32_b32 v0, -1, 0
	v_mbcnt_hi_u32_b32 v0, -1, v0
	v_writelane_b32 v255, s0, 5
	v_or_b32_e32 v0, s61, v0
	s_nop 0
	v_writelane_b32 v255, s1, 6
	v_readfirstlane_b32 s0, v0
	s_ashr_i32 s0, s0, 6
	s_add_i32 s0, s0, s75
	s_cmpk_gt_i32 s0, 0x40ff
	s_cbranch_scc1 .LBB0_81
	s_lshl_b32 s4, s70, 11
	s_lshl_b64 s[2:3], s[4:5], 2
	v_readlane_b32 s6, v254, 5
	v_readlane_b32 s7, v254, 6
	s_add_u32 s2, s6, s2
	v_and_b32_e32 v0, 63, v0
	s_addc_u32 s3, s7, s3
	v_lshlrev_b32_e32 v168, 4, v0
	v_lshl_add_u64 v[36:37], s[2:3], 0, v[168:169]
	s_mov_b64 s[2:3], 0x1000
	v_lshl_add_u64 v[38:39], v[36:37], 0, s[2:3]
	s_mov_b64 s[2:3], 0x1400
	v_lshl_add_u64 v[40:41], v[36:37], 0, s[2:3]
	s_mov_b64 s[2:3], 0x1800
	v_lshl_add_u64 v[42:43], v[36:37], 0, s[2:3]
	s_mov_b64 s[2:3], 0x1c00
	s_ashr_i32 s1, s0, 31
	v_lshl_add_u64 v[44:45], v[36:37], 0, s[2:3]
	s_lshl_b64 s[2:3], s[0:1], 12
	s_add_u32 s2, s82, s2
	v_lshlrev_b32_e32 v168, 3, v0
	s_addc_u32 s3, s86, s3
	v_lshl_add_u64 v[46:47], s[2:3], 0, v[168:169]
	s_lshl_b64 s[2:3], s[0:1], 13
	v_readlane_b32 s1, v255, 4
	s_add_u32 s1, s1, s2
	v_readlane_b32 s2, v255, 3
	s_addc_u32 s3, s2, s3
	v_lshlrev_b32_e32 v168, 4, v0
	global_load_dwordx4 v[114:117], v[36:37], off
	global_load_dwordx4 v[118:121], v[36:37], off offset:1024
	global_load_dwordx4 v[122:125], v[36:37], off offset:2048
	global_load_dwordx4 v[126:129], v[36:37], off offset:3072
	global_load_dwordx4 v[130:133], v[38:39], off
	global_load_dwordx4 v[134:137], v[40:41], off
	global_load_dwordx4 v[138:141], v[42:43], off
	global_load_dwordx4 v[142:145], v[44:45], off
	s_waitcnt vmcnt(0)
	s_branch .LBB0_77

; __device__ __forceinline__ void phase_rmsnorm(const float* __restrict__ src_meta, const float* __restrict__ src_body, const float* __restrict__ w, bf16_t* __restrict__ H, const int wave_s) {
;     ...
;     const float* row = (r < NMETA) ? src_meta + (size_t)r * DM : src_body + (size_t)(r - NMETA) * DM;
;     const f32x4* xr = (const f32x4*)row + lane; f32x4 v[8]; float ss = 0.f;
; #pragma unroll
;     for (int j = 0; j < 8; ++j) { v[j] = xr[64 * j]; ss += (v[j].x * v[j].x + v[j].y * v[j].y) + (v[j].z * v[j].z + v[j].w * v[j].w); }
;     const float rs = rsqrtf(wave_sum(ss) * (1.f / DM) + EPS);
; #pragma unroll
;     for (int j = 0; j < 8; ++j) { const f32x4 g = ((const f32x4*)w)[lane + 64 * j];
.LBB0_77:
	s_cmpk_lt_i32 s0, 0x4010
	s_mov_b64 s[6:7], -1
	s_cbranch_scc0 .LBB0_79
	s_add_i32 s4, s0, -16
	s_lshl_b64 s[6:7], s[4:5], 13
	v_readlane_b32 s8, v255, 5
	v_readlane_b32 s9, v255, 6
	s_add_u32 s2, s8, s6
	s_addc_u32 s4, s9, s7
	s_cmp_lt_i32 s0, 16
	s_cselect_b32 s7, s3, s4
	s_cselect_b32 s6, s1, s2
	global_load_dwordx4 v[28:31], v168, s[6:7]
	global_load_dwordx4 v[24:27], v168, s[6:7] offset:1024
	global_load_dwordx4 v[20:23], v168, s[6:7] offset:2048
	v_lshl_add_u64 v[0:1], s[6:7], 0, v[168:169]
	global_load_dwordx4 v[12:15], v168, s[6:7] offset:3072
	s_movk_i32 s2, 0x1000
	v_add_co_u32_e32 v16, vcc, s2, v0
	s_mov_b64 s[6:7], 0
	s_nop 0
	v_addc_co_u32_e32 v17, vcc, 0, v1, vcc
	global_load_dwordx4 v[4:7], v[16:17], off offset:1024
	global_load_dwordx4 v[8:11], v[16:17], off
	global_load_dwordx4 v[0:3], v[16:17], off offset:3072
	v_cmp_lt_i32_e32 vcc, v198, v197
	s_waitcnt vmcnt(0)
	v_mov_b32_e32 v32, v29
	s_waitcnt vmcnt(5)
	v_mov_b32_e32 v33, v25
	s_waitcnt vmcnt(4)
	v_pk_mul_f32 v[48:49], v[22:23], v[22:23]
	v_pk_mul_f32 v[50:51], v[20:21], v[20:21]
	v_mov_b32_e32 v18, v28
	v_pk_mov_b32 v[52:53], v[50:51], v[48:49] op_sel:[1,0]
	v_mov_b32_e32 v51, v49
	v_mov_b32_e32 v48, v31
	v_mov_b32_e32 v49, v27
	v_mov_b32_e32 v19, v24
	v_mov_b32_e32 v34, v30
	v_mov_b32_e32 v35, v26
	v_pk_mul_f32 v[32:33], v[32:33], v[32:33]
	v_pk_mul_f32 v[48:49], v[48:49], v[48:49]
	v_pk_fma_f32 v[18:19], v[18:19], v[18:19], v[32:33]
	v_pk_fma_f32 v[34:35], v[34:35], v[34:35], v[48:49]
	s_waitcnt vmcnt(3)
	v_mul_f32_e32 v32, v13, v13
	v_pk_add_f32 v[34:35], v[18:19], v[34:35]
	v_mul_f32_e32 v18, v15, v15
	v_pk_fma_f32 v[32:33], v[12:13], v[12:13], v[32:33] op_sel_hi:[1,1,0]
	v_pk_fma_f32 v[18:19], v[14:15], v[14:15], v[18:19] op_sel_hi:[1,1,0]
	s_waitcnt vmcnt(1)
	v_mul_f32_e32 v33, v10, v10
	v_mul_f32_e32 v19, v11, v11
	v_pk_add_f32 v[32:33], v[32:33], v[18:19]
	global_load_dwordx4 v[16:19], v[16:17], off offset:2048
	v_pk_add_f32 v[48:49], v[52:53], v[50:51]
	v_pk_mul_f32 v[50:51], v[6:7], v[6:7]
	v_pk_mul_f32 v[52:53], v[4:5], v[4:5]
	s_waitcnt vmcnt(1)
	v_mul_f32_e32 v56, v2, v2
	v_pk_mov_b32 v[54:55], v[52:53], v[50:51] op_sel:[1,0]
	v_mov_b32_e32 v53, v51
	v_pk_add_f32 v[50:51], v[54:55], v[52:53]
	v_pk_add_f32 v[48:49], v[48:49], v[48:49] op_sel:[0,1] op_sel_hi:[1,0]
	v_pk_add_f32 v[34:35], v[34:35], v[34:35] op_sel:[0,1] op_sel_hi:[1,0]
	s_waitcnt vmcnt(0)
	v_mul_f32_e32 v52, v17, v17
	v_mul_f32_e32 v54, v19, v19
	v_pk_fma_f32 v[52:53], v[16:17], v[16:17], v[52:53] op_sel_hi:[1,1,0]
	v_pk_fma_f32 v[54:55], v[18:19], v[18:19], v[54:55] op_sel_hi:[1,1,0]
	v_mov_b32_e32 v53, v56
	v_mul_f32_e32 v55, v3, v3
	v_pk_add_f32 v[52:53], v[52:53], v[54:55]
	v_mul_f32_e32 v54, v9, v9
	v_mov_b32_e32 v49, v54
	v_mul_f32_e32 v54, v8, v8
	v_mov_b32_e32 v35, v54
	v_pk_add_f32 v[34:35], v[34:35], v[48:49]
	v_mul_f32_e32 v55, v0, v0
	v_pk_add_f32 v[32:33], v[34:35], v[32:33]
	v_mul_f32_e32 v56, v1, v1
	v_pk_add_f32 v[48:49], v[50:51], v[50:51] op_sel:[0,1] op_sel_hi:[1,0]
	v_pk_add_f32 v[32:33], v[32:33], v[32:33] op_sel:[0,1] op_sel_hi:[1,0]
	v_mov_b32_e32 v49, v56
	v_mov_b32_e32 v33, v55
	v_pk_add_f32 v[32:33], v[32:33], v[48:49]
	v_cndmask_b32_e32 v54, v196, v198, vcc
	v_pk_add_f32 v[32:33], v[32:33], v[52:53]
	v_lshlrev_b32_e32 v54, 2, v54
	v_add_f32_e32 v32, v32, v33
	ds_bpermute_b32 v33, v54, v32
	v_cmp_lt_i32_e32 vcc, v199, v197
	v_mov_b32_e32 v50, v114
	v_mov_b32_e32 v51, v115
	v_mov_b32_e32 v52, v116
	v_mov_b32_e32 v53, v117
	v_mov_b32_e32 v54, v28
	v_cndmask_b32_e32 v34, v196, v199, vcc
	v_lshlrev_b32_e32 v34, 2, v34
	s_waitcnt lgkmcnt(0)
	v_add_f32_e32 v32, v32, v33
	ds_bpermute_b32 v33, v34, v32
	v_cmp_lt_i32_e32 vcc, v200, v197
	v_mov_b32_e32 v55, v30
	v_mov_b32_e32 v30, v29
	v_cndmask_b32_e32 v34, v196, v200, vcc
	v_lshlrev_b32_e32 v34, 2, v34
	s_waitcnt lgkmcnt(0)
	v_add_f32_e32 v32, v32, v33
	ds_bpermute_b32 v33, v34, v32
	v_cmp_lt_i32_e32 vcc, v201, v197
	s_waitcnt lgkmcnt(0)
	v_add_f32_e32 v32, v32, v33
	v_cndmask_b32_e32 v34, v196, v201, vcc
	v_lshlrev_b32_e32 v34, 2, v34
	ds_bpermute_b32 v33, v34, v32
	v_cmp_lt_i32_e32 vcc, v202, v197
	s_waitcnt lgkmcnt(0)
	v_add_f32_e32 v32, v32, v33
	v_cndmask_b32_e32 v34, v196, v202, vcc
	v_lshlrev_b32_e32 v34, 2, v34
	ds_bpermute_b32 v33, v34, v32
	v_cmp_lt_i32_e32 vcc, v203, v197
	s_waitcnt lgkmcnt(0)
	v_add_f32_e32 v32, v32, v33
	v_cndmask_b32_e32 v34, v196, v203, vcc
	v_lshlrev_b32_e32 v34, 2, v34
	ds_bpermute_b32 v33, v34, v32
	s_waitcnt lgkmcnt(0)
	v_add_f32_e32 v32, v32, v33
	v_fmamk_f32 v32, v32, 0x3a000000, v170
	v_mul_f32_e32 v33, 0x4b800000, v32
	v_cmp_gt_f32_e32 vcc, s94, v32
	s_nop 1
	v_cndmask_b32_e32 v32, v32, v33, vcc
	v_rsq_f32_e32 v32, v32
	s_nop 0
	v_mul_f32_e32 v28, 0x45800000, v32
	v_cndmask_b32_e32 v48, v32, v28, vcc
	v_mov_b32_e32 v32, v118
	v_mov_b32_e32 v33, v119
	v_mov_b32_e32 v34, v120
	v_mov_b32_e32 v35, v121
	v_pk_mul_f32 v[28:29], v[30:31], v[48:49] op_sel_hi:[1,0]

; __device__ __forceinline__ unsigned pk2(float lo, float hi) { return f2bf(lo) | (f2bf(hi) << 16); }
; __device__ __forceinline__ void phase_rmsnorm(const float* __restrict__ src_meta, const float* __restrict__ src_body, const float* __restrict__ w, bf16_t* __restrict__ H, const int wave_s) {
;     ...
;       o8[64 * j] = (u32x2){pk2(v[j].x * rs * g.x, v[j].y * rs * g.y), pk2(v[j].z * rs * g.z, v[j].w * rs * g.w)}; }
	v_mov_b32_e32 v31, v52
	v_mov_b32_e32 v52, v51
	v_pk_mul_f32 v[28:29], v[52:53], v[28:29]
	v_mov_b32_e32 v53, v26
	v_mov_b32_e32 v26, v25
	v_mov_b32_e32 v30, v50
	v_mov_b32_e32 v52, v24
	v_pk_mul_f32 v[50:51], v[26:27], v[48:49] op_sel_hi:[1,0]
	v_pk_mul_f32 v[26:27], v[54:55], v[48:49] op_sel_hi:[1,0]
	v_pk_mul_f32 v[52:53], v[52:53], v[48:49] op_sel_hi:[1,0]
	v_pk_mul_f32 v[26:27], v[30:31], v[26:27]
	v_and_b32_sdwa v30, v29, v171 dst_sel:DWORD dst_unused:UNUSED_PAD src0_sel:WORD_1 src1_sel:DWORD
	v_and_b32_sdwa v31, v28, v171 dst_sel:DWORD dst_unused:UNUSED_PAD src0_sel:WORD_1 src1_sel:DWORD
	v_add3_u32 v29, v29, v30, s15
	v_add3_u32 v28, v28, v31, s15
	v_and_b32_e32 v29, 0xffff0000, v29
	v_and_b32_e32 v28, 0xffff0000, v28

; __device__ __forceinline__ unsigned pk2(float lo, float hi) { return f2bf(lo) | (f2bf(hi) << 16); }
; __device__ __forceinline__ void phase_rmsnorm(const float* __restrict__ src_meta, const float* __restrict__ src_body, const float* __restrict__ w, bf16_t* __restrict__ H, const int wave_s) {
;     ...
;     for (int j = 0; j < 8; ++j) { const f32x4 g = ((const f32x4*)w)[lane + 64 * j];
;       o8[64 * j] = (u32x2){pk2(v[j].x * rs * g.x, v[j].y * rs * g.y), pk2(v[j].z * rs * g.z, v[j].w * rs * g.w)}; }
	v_mov_b32_e32 v24, v32
	v_mov_b32_e32 v25, v34
	v_pk_mul_f32 v[52:53], v[24:25], v[52:53]
	v_and_b32_sdwa v24, v27, v171 dst_sel:DWORD dst_unused:UNUSED_PAD src0_sel:WORD_1 src1_sel:DWORD
	v_and_b32_sdwa v25, v26, v171 dst_sel:DWORD dst_unused:UNUSED_PAD src0_sel:WORD_1 src1_sel:DWORD
	v_add3_u32 v32, v26, v25, s15
	v_add3_u32 v34, v27, v24, s15
	v_mov_b32_e32 v24, v122
	v_mov_b32_e32 v25, v123
	v_mov_b32_e32 v26, v124
	v_mov_b32_e32 v27, v125
	v_or_b32_sdwa v29, v29, v34 dst_sel:DWORD dst_unused:UNUSED_PAD src0_sel:DWORD src1_sel:WORD_1
	v_or_b32_sdwa v28, v28, v32 dst_sel:DWORD dst_unused:UNUSED_PAD src0_sel:DWORD src1_sel:WORD_1
	global_store_dwordx2 v[46:47], v[28:29], off
	v_mov_b32_e32 v28, v126
	v_mov_b32_e32 v29, v127
	v_mov_b32_e32 v30, v128
	v_mov_b32_e32 v31, v129
	v_mov_b32_e32 v34, v33
	v_pk_mul_f32 v[32:33], v[34:35], v[50:51]
	v_and_b32_sdwa v34, v53, v171 dst_sel:DWORD dst_unused:UNUSED_PAD src0_sel:WORD_1 src1_sel:DWORD
	v_and_b32_sdwa v35, v52, v171 dst_sel:DWORD dst_unused:UNUSED_PAD src0_sel:WORD_1 src1_sel:DWORD
	v_add3_u32 v49, v52, v35, s15
	v_add3_u32 v50, v53, v34, s15
	v_and_b32_sdwa v34, v33, v171 dst_sel:DWORD dst_unused:UNUSED_PAD src0_sel:WORD_1 src1_sel:DWORD
	v_and_b32_sdwa v35, v32, v171 dst_sel:DWORD dst_unused:UNUSED_PAD src0_sel:WORD_1 src1_sel:DWORD
	v_add3_u32 v51, v33, v34, s15
	v_add3_u32 v52, v32, v35, s15
	v_mov_b32_e32 v32, v130
	v_mov_b32_e32 v33, v131
	v_mov_b32_e32 v34, v132
	v_mov_b32_e32 v35, v133
	v_and_b32_e32 v51, 0xffff0000, v51
	v_and_b32_e32 v52, 0xffff0000, v52
	v_or_b32_sdwa v51, v51, v50 dst_sel:DWORD dst_unused:UNUSED_PAD src0_sel:DWORD src1_sel:WORD_1
	v_or_b32_sdwa v50, v52, v49 dst_sel:DWORD dst_unused:UNUSED_PAD src0_sel:DWORD src1_sel:WORD_1
	global_store_dwordx2 v[46:47], v[50:51], off offset:512
	v_mov_b32_e32 v50, v20
	v_mov_b32_e32 v51, v22
	v_pk_mul_f32 v[50:51], v[50:51], v[48:49] op_sel_hi:[1,0]
	v_mov_b32_e32 v22, v21
	v_pk_mul_f32 v[20:21], v[22:23], v[48:49] op_sel_hi:[1,0]
	v_pk_mul_f32 v[0:1], v[0:1], v[48:49] op_sel_hi:[1,0]
	v_pk_mul_f32 v[2:3], v[2:3], v[48:49] op_sel_hi:[1,0]

; __device__ __forceinline__ unsigned pk2(float lo, float hi) { return f2bf(lo) | (f2bf(hi) << 16); }
; __device__ __forceinline__ void phase_rmsnorm(const float* __restrict__ src_meta, const float* __restrict__ src_body, const float* __restrict__ w, bf16_t* __restrict__ H, const int wave_s) {
;     ...
;     for (int j = 0; j < 8; ++j) { const f32x4 g = ((const f32x4*)w)[lane + 64 * j];
;       o8[64 * j] = (u32x2){pk2(v[j].x * rs * g.x, v[j].y * rs * g.y), pk2(v[j].z * rs * g.z, v[j].w * rs * g.w)}; }
	v_mov_b32_e32 v52, v24
	v_mov_b32_e32 v53, v26
	v_pk_mul_f32 v[50:51], v[52:53], v[50:51]
	v_mov_b32_e32 v52, v134
	v_mov_b32_e32 v53, v135
	v_mov_b32_e32 v54, v136
	v_mov_b32_e32 v55, v137
	v_mov_b32_e32 v26, v25
	v_pk_mul_f32 v[20:21], v[26:27], v[20:21]
	v_and_b32_sdwa v22, v51, v171 dst_sel:DWORD dst_unused:UNUSED_PAD src0_sel:WORD_1 src1_sel:DWORD
	v_and_b32_sdwa v23, v50, v171 dst_sel:DWORD dst_unused:UNUSED_PAD src0_sel:WORD_1 src1_sel:DWORD
	v_add3_u32 v24, v50, v23, s15
	v_add3_u32 v25, v51, v22, s15
	v_and_b32_sdwa v22, v21, v171 dst_sel:DWORD dst_unused:UNUSED_PAD src0_sel:WORD_1 src1_sel:DWORD
	v_and_b32_sdwa v23, v20, v171 dst_sel:DWORD dst_unused:UNUSED_PAD src0_sel:WORD_1 src1_sel:DWORD
	v_add3_u32 v26, v21, v22, s15
	v_add3_u32 v27, v20, v23, s15
	v_mov_b32_e32 v20, v138
	v_mov_b32_e32 v21, v139
	v_mov_b32_e32 v22, v140
	v_mov_b32_e32 v23, v141
	v_and_b32_e32 v26, 0xffff0000, v26
	v_and_b32_e32 v27, 0xffff0000, v27
	v_or_b32_sdwa v25, v26, v25 dst_sel:DWORD dst_unused:UNUSED_PAD src0_sel:DWORD src1_sel:WORD_1
	v_or_b32_sdwa v24, v27, v24 dst_sel:DWORD dst_unused:UNUSED_PAD src0_sel:DWORD src1_sel:WORD_1
	global_store_dwordx2 v[46:47], v[24:25], off offset:1024
	v_mov_b32_e32 v24, v12
	v_mov_b32_e32 v25, v14
	v_pk_mul_f32 v[24:25], v[24:25], v[48:49] op_sel_hi:[1,0]

; __device__ __forceinline__ unsigned pk2(float lo, float hi) { return f2bf(lo) | (f2bf(hi) << 16); }
; __device__ __forceinline__ void phase_rmsnorm(const float* __restrict__ src_meta, const float* __restrict__ src_body, const float* __restrict__ w, bf16_t* __restrict__ H, const int wave_s) {
;     ...
;     for (int j = 0; j < 8; ++j) { const f32x4 g = ((const f32x4*)w)[lane + 64 * j];
;       o8[64 * j] = (u32x2){pk2(v[j].x * rs * g.x, v[j].y * rs * g.y), pk2(v[j].z * rs * g.z, v[j].w * rs * g.w)}; }
	v_mov_b32_e32 v26, v28
	v_mov_b32_e32 v27, v30
	v_mov_b32_e32 v14, v13
	v_pk_mul_f32 v[24:25], v[26:27], v[24:25]
	v_pk_mul_f32 v[12:13], v[14:15], v[48:49] op_sel_hi:[1,0]
	v_mov_b32_e32 v30, v29
	v_pk_mul_f32 v[26:27], v[30:31], v[12:13]
	v_and_b32_sdwa v12, v25, v171 dst_sel:DWORD dst_unused:UNUSED_PAD src0_sel:WORD_1 src1_sel:DWORD
	v_and_b32_sdwa v13, v24, v171 dst_sel:DWORD dst_unused:UNUSED_PAD src0_sel:WORD_1 src1_sel:DWORD
	v_add3_u32 v24, v24, v13, s15
	v_add3_u32 v25, v25, v12, s15
	v_mov_b32_e32 v12, v142
	v_mov_b32_e32 v13, v143
	v_mov_b32_e32 v14, v144
	v_mov_b32_e32 v15, v145
	v_and_b32_sdwa v28, v27, v171 dst_sel:DWORD dst_unused:UNUSED_PAD src0_sel:WORD_1 src1_sel:DWORD
	v_and_b32_sdwa v29, v26, v171 dst_sel:DWORD dst_unused:UNUSED_PAD src0_sel:WORD_1 src1_sel:DWORD
	v_add3_u32 v27, v27, v28, s15
	v_add3_u32 v26, v26, v29, s15
	v_and_b32_e32 v27, 0xffff0000, v27
	v_and_b32_e32 v26, 0xffff0000, v26
	v_or_b32_sdwa v25, v27, v25 dst_sel:DWORD dst_unused:UNUSED_PAD src0_sel:DWORD src1_sel:WORD_1
	v_or_b32_sdwa v24, v26, v24 dst_sel:DWORD dst_unused:UNUSED_PAD src0_sel:DWORD src1_sel:WORD_1
	global_store_dwordx2 v[46:47], v[24:25], off offset:1536
	v_mov_b32_e32 v24, v8
	v_mov_b32_e32 v25, v10
	v_pk_mul_f32 v[24:25], v[24:25], v[48:49] op_sel_hi:[1,0]

; __device__ __forceinline__ unsigned pk2(float lo, float hi) { return f2bf(lo) | (f2bf(hi) << 16); }
; __device__ __forceinline__ void phase_rmsnorm(const float* __restrict__ src_meta, const float* __restrict__ src_body, const float* __restrict__ w, bf16_t* __restrict__ H, const int wave_s) {
;     ...
;     for (int j = 0; j < 8; ++j) { const f32x4 g = ((const f32x4*)w)[lane + 64 * j];
;       o8[64 * j] = (u32x2){pk2(v[j].x * rs * g.x, v[j].y * rs * g.y), pk2(v[j].z * rs * g.z, v[j].w * rs * g.w)}; }
	v_mov_b32_e32 v26, v32
	v_mov_b32_e32 v27, v34
	v_mov_b32_e32 v10, v9
	v_pk_mul_f32 v[24:25], v[26:27], v[24:25]
	v_pk_mul_f32 v[8:9], v[10:11], v[48:49] op_sel_hi:[1,0]
	v_mov_b32_e32 v34, v33
	v_pk_mul_f32 v[8:9], v[34:35], v[8:9]
	v_and_b32_sdwa v10, v25, v171 dst_sel:DWORD dst_unused:UNUSED_PAD src0_sel:WORD_1 src1_sel:DWORD
	v_and_b32_sdwa v11, v24, v171 dst_sel:DWORD dst_unused:UNUSED_PAD src0_sel:WORD_1 src1_sel:DWORD
	v_add3_u32 v11, v24, v11, s15
	v_add3_u32 v10, v25, v10, s15
	v_and_b32_sdwa v24, v9, v171 dst_sel:DWORD dst_unused:UNUSED_PAD src0_sel:WORD_1 src1_sel:DWORD
	v_and_b32_sdwa v25, v8, v171 dst_sel:DWORD dst_unused:UNUSED_PAD src0_sel:WORD_1 src1_sel:DWORD
	v_add3_u32 v9, v9, v24, s15
	v_add3_u32 v8, v8, v25, s15
	v_and_b32_e32 v9, 0xffff0000, v9
	v_and_b32_e32 v8, 0xffff0000, v8
	v_or_b32_sdwa v9, v9, v10 dst_sel:DWORD dst_unused:UNUSED_PAD src0_sel:DWORD src1_sel:WORD_1
	v_or_b32_sdwa v8, v8, v11 dst_sel:DWORD dst_unused:UNUSED_PAD src0_sel:DWORD src1_sel:WORD_1
	global_store_dwordx2 v[46:47], v[8:9], off offset:2048
	v_mov_b32_e32 v8, v4
	v_mov_b32_e32 v9, v6
	v_pk_mul_f32 v[8:9], v[8:9], v[48:49] op_sel_hi:[1,0]
	v_mov_b32_e32 v6, v5
	v_pk_mul_f32 v[4:5], v[6:7], v[48:49] op_sel_hi:[1,0]

; __device__ __forceinline__ unsigned pk2(float lo, float hi) { return f2bf(lo) | (f2bf(hi) << 16); }
; __device__ __forceinline__ void phase_rmsnorm(const float* __restrict__ src_meta, const float* __restrict__ src_body, const float* __restrict__ w, bf16_t* __restrict__ H, const int wave_s) {
;     ...
;     for (int j = 0; j < 8; ++j) { const f32x4 g = ((const f32x4*)w)[lane + 64 * j];
;       o8[64 * j] = (u32x2){pk2(v[j].x * rs * g.x, v[j].y * rs * g.y), pk2(v[j].z * rs * g.z, v[j].w * rs * g.w)}; }
	v_mov_b32_e32 v10, v52
	v_mov_b32_e32 v11, v54
	v_pk_mul_f32 v[8:9], v[8:9], v[10:11]
	v_mov_b32_e32 v54, v53
	v_pk_mul_f32 v[4:5], v[4:5], v[54:55]
	v_and_b32_sdwa v6, v9, v171 dst_sel:DWORD dst_unused:UNUSED_PAD src0_sel:WORD_1 src1_sel:DWORD
	v_and_b32_sdwa v7, v8, v171 dst_sel:DWORD dst_unused:UNUSED_PAD src0_sel:WORD_1 src1_sel:DWORD
	v_add3_u32 v7, v8, v7, s15
	v_add3_u32 v6, v9, v6, s15
	v_and_b32_sdwa v8, v5, v171 dst_sel:DWORD dst_unused:UNUSED_PAD src0_sel:WORD_1 src1_sel:DWORD
	v_and_b32_sdwa v9, v4, v171 dst_sel:DWORD dst_unused:UNUSED_PAD src0_sel:WORD_1 src1_sel:DWORD
	v_add3_u32 v5, v5, v8, s15
	v_add3_u32 v4, v4, v9, s15
	v_and_b32_e32 v5, 0xffff0000, v5
	v_and_b32_e32 v4, 0xffff0000, v4
	v_or_b32_sdwa v5, v5, v6 dst_sel:DWORD dst_unused:UNUSED_PAD src0_sel:DWORD src1_sel:WORD_1
	v_or_b32_sdwa v4, v4, v7 dst_sel:DWORD dst_unused:UNUSED_PAD src0_sel:DWORD src1_sel:WORD_1
	global_store_dwordx2 v[46:47], v[4:5], off offset:2560
	v_mov_b32_e32 v4, v16
	v_mov_b32_e32 v5, v18
	v_pk_mul_f32 v[4:5], v[4:5], v[48:49] op_sel_hi:[1,0]

; __device__ __forceinline__ unsigned pk2(float lo, float hi) { return f2bf(lo) | (f2bf(hi) << 16); }
; __device__ __forceinline__ void phase_rmsnorm(const float* __restrict__ src_meta, const float* __restrict__ src_body, const float* __restrict__ w, bf16_t* __restrict__ H, const int wave_s) {
;     ...
;     for (int j = 0; j < 8; ++j) { const f32x4 g = ((const f32x4*)w)[lane + 64 * j];
;       o8[64 * j] = (u32x2){pk2(v[j].x * rs * g.x, v[j].y * rs * g.y), pk2(v[j].z * rs * g.z, v[j].w * rs * g.w)}; }
	v_mov_b32_e32 v6, v20
	v_mov_b32_e32 v7, v22
	v_mov_b32_e32 v18, v17
	v_pk_mul_f32 v[4:5], v[4:5], v[6:7]
	v_pk_mul_f32 v[6:7], v[18:19], v[48:49] op_sel_hi:[1,0]
	v_mov_b32_e32 v22, v21
	v_pk_mul_f32 v[6:7], v[6:7], v[22:23]
	v_and_b32_sdwa v8, v5, v171 dst_sel:DWORD dst_unused:UNUSED_PAD src0_sel:WORD_1 src1_sel:DWORD
	v_and_b32_sdwa v9, v4, v171 dst_sel:DWORD dst_unused:UNUSED_PAD src0_sel:WORD_1 src1_sel:DWORD
	v_add3_u32 v4, v4, v9, s15
	v_add3_u32 v5, v5, v8, s15
	v_and_b32_sdwa v8, v7, v171 dst_sel:DWORD dst_unused:UNUSED_PAD src0_sel:WORD_1 src1_sel:DWORD
	v_and_b32_sdwa v9, v6, v171 dst_sel:DWORD dst_unused:UNUSED_PAD src0_sel:WORD_1 src1_sel:DWORD
	v_add3_u32 v7, v7, v8, s15
	v_add3_u32 v6, v6, v9, s15
	v_and_b32_e32 v7, 0xffff0000, v7
	v_and_b32_e32 v6, 0xffff0000, v6
	v_or_b32_sdwa v5, v7, v5 dst_sel:DWORD dst_unused:UNUSED_PAD src0_sel:DWORD src1_sel:WORD_1
	v_or_b32_sdwa v4, v6, v4 dst_sel:DWORD dst_unused:UNUSED_PAD src0_sel:DWORD src1_sel:WORD_1

; __device__ __forceinline__ unsigned pk2(float lo, float hi) { return f2bf(lo) | (f2bf(hi) << 16); }
; __device__ __forceinline__ void phase_rmsnorm(const float* __restrict__ src_meta, const float* __restrict__ src_body, const float* __restrict__ w, bf16_t* __restrict__ H, const int wave_s) {
;     ...
;     for (int j = 0; j < 8; ++j) { const f32x4 g = ((const f32x4*)w)[lane + 64 * j];
;       o8[64 * j] = (u32x2){pk2(v[j].x * rs * g.x, v[j].y * rs * g.y), pk2(v[j].z * rs * g.z, v[j].w * rs * g.w)}; }
	v_pk_mul_f32 v[0:1], v[0:1], v[12:13]
	global_store_dwordx2 v[46:47], v[4:5], off offset:3072
	v_and_b32_sdwa v5, v0, v171 dst_sel:DWORD dst_unused:UNUSED_PAD src0_sel:WORD_1 src1_sel:DWORD
	v_and_b32_sdwa v4, v1, v171 dst_sel:DWORD dst_unused:UNUSED_PAD src0_sel:WORD_1 src1_sel:DWORD
	v_add3_u32 v0, v0, v5, s15
	v_pk_mul_f32 v[2:3], v[2:3], v[14:15]
	v_add3_u32 v1, v1, v4, s15
	v_lshrrev_b32_e32 v0, 16, v0
	v_and_b32_sdwa v4, v2, v171 dst_sel:DWORD dst_unused:UNUSED_PAD src0_sel:WORD_1 src1_sel:DWORD
	v_and_or_b32 v0, v1, s14, v0
	v_and_b32_sdwa v1, v3, v171 dst_sel:DWORD dst_unused:UNUSED_PAD src0_sel:WORD_1 src1_sel:DWORD
	v_add3_u32 v2, v2, v4, s15
	v_add3_u32 v1, v3, v1, s15
	v_lshrrev_b32_e32 v2, 16, v2
	v_and_or_b32 v1, v1, s14, v2
